# pass 2 level 1 folded into level 2 (one phase and one grid barrier fewer per even layer)
# baseline (speedup 1.0000x reference)
; __host__ __device__ inline bool phase_is_nop(int ph) {
;     if (ph >= DEPTH * OPS_PER_LAYER) return false;
;     const int layer = ph / OPS_PER_LAYER, op = ph % OPS_PER_LAYER;
;     return ((layer & 1) && ((op >= 10 && op <= 14) || op == 8)) || (layer == 0 && op == 7);
; }
; __global__ void __launch_bounds__(NTHREADS, 2) mega_fwd(Params P) {
;     ...
;     for (int ph = ph_lo; ph < ph_hi; ++ph) {
;         if (phase_is_nop(ph)) continue;
.LBB0_32:
	s_mov_b64 s[4:5], 0
	s_and_b64 vcc, exec, s[2:3]
	s_mov_b64 s[2:3], 0
	s_cbranch_vccz .LBB0_34
	s_add_i32 s50, s60, 18
	s_cmp_gt_u32 s50, 36
	s_cselect_b64 s[2:3], -1, 0
	s_cmp_lg_u32 s67, 7
	s_cselect_b64 s[6:7], -1, 0
	s_or_b64 s[2:3], s[2:3], s[6:7]
	s_cmp_lg_u32 s67, 10
	s_cselect_b64 s[6:7], -1, 0
	s_and_b64 s[2:3], s[2:3], s[6:7]

; template <bool HAS_C, bool STORE_STEPS>
; __device__ __forceinline__ void chain16(f32x4 (&acc)[4], const float* Mb, size_t mstride, float* Cb, size_t cstride, int nsteps) {
;     f32x4 mc[16];
; #pragma unroll
;     for (int i = 0; i < 16; ++i) mc[i] = *(const f32x4*)(Mb + (size_t)i * 64);
;     f32x4 qn[4];
;     if (HAS_C) {
; #pragma unroll
;         for (int j = 0; j < 4; ++j) qn[j] = *(const f32x4*)(Cb + 4 * j);
;     }
;     for (int c = 0; c < nsteps; ++c) {
;         float* cp = Cb + (size_t)c * cstride;
;         f32x4 q[4];
;         if (HAS_C) {
; #pragma unroll
;             for (int j = 0; j < 4; ++j) q[j] = qn[j];
;             const float* cn = Cb + (size_t)(c + 1 < nsteps ? c + 1 : c) * cstride;
; #pragma unroll
;             for (int j = 0; j < 4; ++j) qn[j] = *(const f32x4*)(cn + 4 * j);
;         }
;         f32x4 mn[16];
;         const float* Mn = Mb + (size_t)(c + 1 < nsteps ? c + 1 : c) * mstride;
; #pragma unroll
;         for (int i = 0; i < 16; ++i) mn[i] = *(const f32x4*)(Mn + (size_t)i * 64);
; __device__ __forceinline__ void stage_rwkv_pass2(const Params& P, int level) {
;     ...
;         for (int it0 = spread ? (wave < 2 ? (int)blockIdx.x : P2_NG * 32) : gw; it0 < P2_NG * 8 * 4; it0 += spread ? P2_NG * 32 : ngw) {
;             int it = it0;
;             if (spread) { const int x = blockIdx.x & 7, j = blockIdx.x >> 3, idx = wave * 32 + j; it = ((idx >> 2) * 8 + x) * 4 + (idx & 3); }
;             const int g = it >> 5, h = (it >> 2) & 7, s = it & 3, v = 16 * s + rho;
;             const float* sg = CG + ((size_t)g * 8 + h) * 4096 + (size_t)v * 64 + 16 * g4;
;             f32x4 q[4];
; #pragma unroll
;             for (int j = 0; j < 4; ++j) q[j] = *(const f32x4*)(sg + 4 * j);
; #pragma unroll
;             for (int n = 0; n < 4; ++n) acc[n] = (f32x4){q[0][n], q[1][n], q[2][n], q[3][n]};
;             const float* Mb = MCM + ((size_t)(g * P2_GS) * 8 + h) * 4096 + (size_t)(16 * g4) * 64 + 4 * rho;
;             float* Cb = MCC + ((size_t)(g * P2_GS) * 8 + h) * 4096 + (size_t)v * 64 + 16 * g4;
;             chain16<true, true>(acc, Mb, 32768, Cb, 32768, P2_GS);
.Lp2l2_map:
	s_lshr_b32 s14, s13, 5
	s_bfe_u32 s15, s13, 0x30002
	s_and_b32 s17, s13, 3
	s_lshl_b32 s19, s17, 12
	s_lshl_b32 s18, s15, 14
	s_add_u32 s0, s72, 0x14884000
	s_addc_u32 s1, s73, 0
	s_add_u32 s0, s0, s18
	s_addc_u32 s1, s1, 0
	s_add_u32 s2, s72, 0x14a84000
	s_addc_u32 s3, s73, 0
	s_add_u32 s2, s2, s18
	s_addc_u32 s3, s3, 0
	s_add_u32 s2, s2, s19
	s_addc_u32 s3, s3, 0
	s_mov_b32 s20, s14
	v_mov_b32_e32 v128, 0
	v_mov_b32_e32 v129, 0
	v_mov_b32_e32 v130, 0
	v_mov_b32_e32 v131, 0
	v_mov_b32_e32 v132, 0
	v_mov_b32_e32 v133, 0
	v_mov_b32_e32 v134, 0
	v_mov_b32_e32 v135, 0
	v_mov_b32_e32 v136, 0
	v_mov_b32_e32 v137, 0
	v_mov_b32_e32 v138, 0
	v_mov_b32_e32 v139, 0
	v_mov_b32_e32 v140, 0
	v_mov_b32_e32 v141, 0
	v_mov_b32_e32 v142, 0
	v_mov_b32_e32 v143, 0
	s_cmp_eq_u32 s20, 0
	s_cbranch_scc1 .Lp2_l2g_done
	global_load_dwordx4 v[0:3], v144, s[0:1]
	global_load_dwordx4 v[4:7], v144, s[0:1] offset:256
	global_load_dwordx4 v[8:11], v144, s[0:1] offset:512
	global_load_dwordx4 v[12:15], v144, s[0:1] offset:768
	global_load_dwordx4 v[16:19], v144, s[0:1] offset:1024
	global_load_dwordx4 v[20:23], v144, s[0:1] offset:1280
	global_load_dwordx4 v[24:27], v144, s[0:1] offset:1536
	global_load_dwordx4 v[28:31], v144, s[0:1] offset:1792
	global_load_dwordx4 v[32:35], v144, s[0:1] offset:2048
	global_load_dwordx4 v[36:39], v144, s[0:1] offset:2304
	global_load_dwordx4 v[40:43], v144, s[0:1] offset:2560
	global_load_dwordx4 v[44:47], v144, s[0:1] offset:2816
	global_load_dwordx4 v[48:51], v144, s[0:1] offset:3072
	global_load_dwordx4 v[52:55], v144, s[0:1] offset:3328
	global_load_dwordx4 v[56:59], v144, s[0:1] offset:3584
	global_load_dwordx4 v[60:63], v144, s[0:1] offset:3840
	global_load_dwordx4 v[184:187], v145, s[2:3]
	global_load_dwordx4 v[188:191], v145, s[2:3] offset:16
	global_load_dwordx4 v[192:195], v145, s[2:3] offset:32
	global_load_dwordx4 v[196:199], v145, s[2:3] offset:48
	s_lshr_b32 s21, s20, 1
	s_mov_b32 s9, 0
.Lp2_l2g_loop:
	s_cmp_eq_u32 s9, s21
	s_cbranch_scc1 .Lp2_l2g_tail
	s_mov_b32 s10, 0x20000
	s_add_u32 s4, s0, s10
	s_addc_u32 s5, s1, 0
	s_add_u32 s6, s2, s10
	s_addc_u32 s7, s3, 0
	global_load_dwordx4 v[64:67], v144, s[4:5]
	global_load_dwordx4 v[68:71], v144, s[4:5] offset:256
	global_load_dwordx4 v[72:75], v144, s[4:5] offset:512
	global_load_dwordx4 v[76:79], v144, s[4:5] offset:768
	global_load_dwordx4 v[80:83], v144, s[4:5] offset:1024
	global_load_dwordx4 v[84:87], v144, s[4:5] offset:1280
	global_load_dwordx4 v[88:91], v144, s[4:5] offset:1536
	global_load_dwordx4 v[92:95], v144, s[4:5] offset:1792
	global_load_dwordx4 v[96:99], v144, s[4:5] offset:2048
	global_load_dwordx4 v[100:103], v144, s[4:5] offset:2304
	global_load_dwordx4 v[104:107], v144, s[4:5] offset:2560
	global_load_dwordx4 v[108:111], v144, s[4:5] offset:2816
	global_load_dwordx4 v[112:115], v144, s[4:5] offset:3072
	global_load_dwordx4 v[116:119], v144, s[4:5] offset:3328
	global_load_dwordx4 v[120:123], v144, s[4:5] offset:3584
	global_load_dwordx4 v[124:127], v144, s[4:5] offset:3840
	global_load_dwordx4 v[200:203], v145, s[6:7]
	global_load_dwordx4 v[204:207], v145, s[6:7] offset:16
	global_load_dwordx4 v[212:215], v145, s[6:7] offset:32
	global_load_dwordx4 v[230:233], v145, s[6:7] offset:48
	s_waitcnt vmcnt(20)
	v_mov_b32_e32 v168, v184
	v_mov_b32_e32 v169, v188
	v_mov_b32_e32 v170, v192
	v_mov_b32_e32 v171, v196
	v_mov_b32_e32 v172, v185
	v_mov_b32_e32 v173, v189
	v_mov_b32_e32 v174, v193
	v_mov_b32_e32 v175, v197
	v_mov_b32_e32 v176, v186
	v_mov_b32_e32 v177, v190
	v_mov_b32_e32 v178, v194
	v_mov_b32_e32 v179, v198
	v_mov_b32_e32 v180, v187
	v_mov_b32_e32 v181, v191
	v_mov_b32_e32 v182, v195
	v_mov_b32_e32 v183, v199
	v_mfma_f32_16x16x4_f32 v[168:171], v0, v128, v[168:171]
	v_mfma_f32_16x16x4_f32 v[172:175], v1, v128, v[172:175]
	v_mfma_f32_16x16x4_f32 v[176:179], v2, v128, v[176:179]
	v_mfma_f32_16x16x4_f32 v[180:183], v3, v128, v[180:183]
	v_mfma_f32_16x16x4_f32 v[168:171], v16, v129, v[168:171]
	v_mfma_f32_16x16x4_f32 v[172:175], v17, v129, v[172:175]
	v_mfma_f32_16x16x4_f32 v[176:179], v18, v129, v[176:179]
	v_mfma_f32_16x16x4_f32 v[180:183], v19, v129, v[180:183]
	v_mfma_f32_16x16x4_f32 v[168:171], v32, v130, v[168:171]
	v_mfma_f32_16x16x4_f32 v[172:175], v33, v130, v[172:175]
	v_mfma_f32_16x16x4_f32 v[176:179], v34, v130, v[176:179]
	v_mfma_f32_16x16x4_f32 v[180:183], v35, v130, v[180:183]
	v_mfma_f32_16x16x4_f32 v[168:171], v48, v131, v[168:171]
	v_mfma_f32_16x16x4_f32 v[172:175], v49, v131, v[172:175]
	v_mfma_f32_16x16x4_f32 v[176:179], v50, v131, v[176:179]
	v_mfma_f32_16x16x4_f32 v[180:183], v51, v131, v[180:183]
	v_mfma_f32_16x16x4_f32 v[168:171], v4, v132, v[168:171]
	v_mfma_f32_16x16x4_f32 v[172:175], v5, v132, v[172:175]
	v_mfma_f32_16x16x4_f32 v[176:179], v6, v132, v[176:179]
	v_mfma_f32_16x16x4_f32 v[180:183], v7, v132, v[180:183]
	v_mfma_f32_16x16x4_f32 v[168:171], v20, v133, v[168:171]
	v_mfma_f32_16x16x4_f32 v[172:175], v21, v133, v[172:175]
	v_mfma_f32_16x16x4_f32 v[176:179], v22, v133, v[176:179]
	v_mfma_f32_16x16x4_f32 v[180:183], v23, v133, v[180:183]
	v_mfma_f32_16x16x4_f32 v[168:171], v36, v134, v[168:171]
	v_mfma_f32_16x16x4_f32 v[172:175], v37, v134, v[172:175]
	v_mfma_f32_16x16x4_f32 v[176:179], v38, v134, v[176:179]
	v_mfma_f32_16x16x4_f32 v[180:183], v39, v134, v[180:183]
	v_mfma_f32_16x16x4_f32 v[168:171], v52, v135, v[168:171]
	v_mfma_f32_16x16x4_f32 v[172:175], v53, v135, v[172:175]
	v_mfma_f32_16x16x4_f32 v[176:179], v54, v135, v[176:179]
	v_mfma_f32_16x16x4_f32 v[180:183], v55, v135, v[180:183]
	v_mfma_f32_16x16x4_f32 v[168:171], v8, v136, v[168:171]
	v_mfma_f32_16x16x4_f32 v[172:175], v9, v136, v[172:175]
; template <bool HAS_C, bool STORE_STEPS>
; __device__ __forceinline__ void chain16(f32x4 (&acc)[4], const float* Mb, size_t mstride, float* Cb, size_t cstride, int nsteps) {
;     ...
;     for (int c = 0; c < nsteps; ++c) {
;         float* cp = Cb + (size_t)c * cstride;
;         f32x4 q[4];
;         if (HAS_C) {
; #pragma unroll
;             for (int j = 0; j < 4; ++j) q[j] = qn[j];
;             const float* cn = Cb + (size_t)(c + 1 < nsteps ? c + 1 : c) * cstride;
; #pragma unroll
;             for (int j = 0; j < 4; ++j) qn[j] = *(const f32x4*)(cn + 4 * j);
;         }
;         f32x4 mn[16];
;         const float* Mn = Mb + (size_t)(c + 1 < nsteps ? c + 1 : c) * mstride;
; #pragma unroll
;         for (int i = 0; i < 16; ++i) mn[i] = *(const f32x4*)(Mn + (size_t)i * 64);
;         if (STORE_STEPS) {
; #pragma unroll
;             for (int j = 0; j < 4; ++j) *(f32x4*)(cp + 4 * j) = (f32x4){acc[0][j], acc[1][j], acc[2][j], acc[3][j]};
;         }
;         f32x4 na[4];
; #pragma unroll
;         for (int n = 0; n < 4; ++n) na[n] = HAS_C ? (f32x4){q[0][n], q[1][n], q[2][n], q[3][n]} : (f32x4){0.f, 0.f, 0.f, 0.f};
; #pragma unroll
;         for (int n = 0; n < 4; ++n)
; #pragma unroll
;             for (int j = 0; j < 4; ++j) {
;                 const f32x4 a4 = mc[4 * j + n];
; #pragma unroll
;                 for (int np = 0; np < 4; ++np) na[np] = __builtin_amdgcn_mfma_f32_16x16x4f32(a4[np], acc[n][j], na[np], 0, 0, 0);
;             }
; #pragma unroll
;         for (int n = 0; n < 4; ++n) acc[n] = na[n];
; #pragma unroll
;         for (int i = 0; i < 16; ++i) mc[i] = mn[i];
;     }
	v_mfma_f32_16x16x4_f32 v[176:179], v10, v136, v[176:179]
	v_mfma_f32_16x16x4_f32 v[180:183], v11, v136, v[180:183]
	v_mfma_f32_16x16x4_f32 v[168:171], v24, v137, v[168:171]
	v_mfma_f32_16x16x4_f32 v[172:175], v25, v137, v[172:175]
	v_mfma_f32_16x16x4_f32 v[176:179], v26, v137, v[176:179]
	v_mfma_f32_16x16x4_f32 v[180:183], v27, v137, v[180:183]
	v_mfma_f32_16x16x4_f32 v[168:171], v40, v138, v[168:171]
	v_mfma_f32_16x16x4_f32 v[172:175], v41, v138, v[172:175]
	v_mfma_f32_16x16x4_f32 v[176:179], v42, v138, v[176:179]
	v_mfma_f32_16x16x4_f32 v[180:183], v43, v138, v[180:183]
	v_mfma_f32_16x16x4_f32 v[168:171], v56, v139, v[168:171]
	v_mfma_f32_16x16x4_f32 v[172:175], v57, v139, v[172:175]
	v_mfma_f32_16x16x4_f32 v[176:179], v58, v139, v[176:179]
	v_mfma_f32_16x16x4_f32 v[180:183], v59, v139, v[180:183]
	v_mfma_f32_16x16x4_f32 v[168:171], v12, v140, v[168:171]
	v_mfma_f32_16x16x4_f32 v[172:175], v13, v140, v[172:175]
	v_mfma_f32_16x16x4_f32 v[176:179], v14, v140, v[176:179]
	v_mfma_f32_16x16x4_f32 v[180:183], v15, v140, v[180:183]
	v_mfma_f32_16x16x4_f32 v[168:171], v28, v141, v[168:171]
	v_mfma_f32_16x16x4_f32 v[172:175], v29, v141, v[172:175]
	v_mfma_f32_16x16x4_f32 v[176:179], v30, v141, v[176:179]
	v_mfma_f32_16x16x4_f32 v[180:183], v31, v141, v[180:183]
	v_mfma_f32_16x16x4_f32 v[168:171], v44, v142, v[168:171]
	v_mfma_f32_16x16x4_f32 v[172:175], v45, v142, v[172:175]
	v_mfma_f32_16x16x4_f32 v[176:179], v46, v142, v[176:179]
	v_mfma_f32_16x16x4_f32 v[180:183], v47, v142, v[180:183]
	v_mfma_f32_16x16x4_f32 v[168:171], v60, v143, v[168:171]
	v_mfma_f32_16x16x4_f32 v[172:175], v61, v143, v[172:175]
	v_mfma_f32_16x16x4_f32 v[176:179], v62, v143, v[176:179]
	v_mfma_f32_16x16x4_f32 v[180:183], v63, v143, v[180:183]
	s_mov_b64 s[0:1], s[4:5]
	s_mov_b64 s[2:3], s[6:7]
	s_mov_b32 s10, 0x20000
	s_add_u32 s4, s0, s10
	s_addc_u32 s5, s1, 0
	s_add_u32 s6, s2, s10
	s_addc_u32 s7, s3, 0
	global_load_dwordx4 v[0:3], v144, s[4:5]
	global_load_dwordx4 v[4:7], v144, s[4:5] offset:256
	global_load_dwordx4 v[8:11], v144, s[4:5] offset:512
	global_load_dwordx4 v[12:15], v144, s[4:5] offset:768
	global_load_dwordx4 v[16:19], v144, s[4:5] offset:1024
	global_load_dwordx4 v[20:23], v144, s[4:5] offset:1280
	global_load_dwordx4 v[24:27], v144, s[4:5] offset:1536
	global_load_dwordx4 v[28:31], v144, s[4:5] offset:1792
	global_load_dwordx4 v[32:35], v144, s[4:5] offset:2048
	global_load_dwordx4 v[36:39], v144, s[4:5] offset:2304
	global_load_dwordx4 v[40:43], v144, s[4:5] offset:2560
	global_load_dwordx4 v[44:47], v144, s[4:5] offset:2816
	global_load_dwordx4 v[48:51], v144, s[4:5] offset:3072
	global_load_dwordx4 v[52:55], v144, s[4:5] offset:3328
	global_load_dwordx4 v[56:59], v144, s[4:5] offset:3584
	global_load_dwordx4 v[60:63], v144, s[4:5] offset:3840
	global_load_dwordx4 v[184:187], v145, s[6:7]
	global_load_dwordx4 v[188:191], v145, s[6:7] offset:16
	global_load_dwordx4 v[192:195], v145, s[6:7] offset:32
	global_load_dwordx4 v[196:199], v145, s[6:7] offset:48
	s_waitcnt vmcnt(20)
	v_mov_b32_e32 v128, v200
	v_mov_b32_e32 v129, v204
	v_mov_b32_e32 v130, v212
	v_mov_b32_e32 v131, v230
	v_mov_b32_e32 v132, v201
	v_mov_b32_e32 v133, v205
	v_mov_b32_e32 v134, v213
	v_mov_b32_e32 v135, v231
	v_mov_b32_e32 v136, v202
	v_mov_b32_e32 v137, v206
	v_mov_b32_e32 v138, v214
	v_mov_b32_e32 v139, v232
	v_mov_b32_e32 v140, v203
	v_mov_b32_e32 v141, v207
	v_mov_b32_e32 v142, v215
	v_mov_b32_e32 v143, v233
	v_mfma_f32_16x16x4_f32 v[128:131], v64, v168, v[128:131]
	v_mfma_f32_16x16x4_f32 v[132:135], v65, v168, v[132:135]
	v_mfma_f32_16x16x4_f32 v[136:139], v66, v168, v[136:139]
	v_mfma_f32_16x16x4_f32 v[140:143], v67, v168, v[140:143]
	v_mfma_f32_16x16x4_f32 v[128:131], v80, v169, v[128:131]
	v_mfma_f32_16x16x4_f32 v[132:135], v81, v169, v[132:135]
	v_mfma_f32_16x16x4_f32 v[136:139], v82, v169, v[136:139]
	v_mfma_f32_16x16x4_f32 v[140:143], v83, v169, v[140:143]
	v_mfma_f32_16x16x4_f32 v[128:131], v96, v170, v[128:131]
	v_mfma_f32_16x16x4_f32 v[132:135], v97, v170, v[132:135]
	v_mfma_f32_16x16x4_f32 v[136:139], v98, v170, v[136:139]
	v_mfma_f32_16x16x4_f32 v[140:143], v99, v170, v[140:143]
	v_mfma_f32_16x16x4_f32 v[128:131], v112, v171, v[128:131]
	v_mfma_f32_16x16x4_f32 v[132:135], v113, v171, v[132:135]
	v_mfma_f32_16x16x4_f32 v[136:139], v114, v171, v[136:139]
	v_mfma_f32_16x16x4_f32 v[140:143], v115, v171, v[140:143]
	v_mfma_f32_16x16x4_f32 v[128:131], v68, v172, v[128:131]
	v_mfma_f32_16x16x4_f32 v[132:135], v69, v172, v[132:135]
	v_mfma_f32_16x16x4_f32 v[136:139], v70, v172, v[136:139]
	v_mfma_f32_16x16x4_f32 v[140:143], v71, v172, v[140:143]
	v_mfma_f32_16x16x4_f32 v[128:131], v84, v173, v[128:131]
	v_mfma_f32_16x16x4_f32 v[132:135], v85, v173, v[132:135]
	v_mfma_f32_16x16x4_f32 v[136:139], v86, v173, v[136:139]
	v_mfma_f32_16x16x4_f32 v[140:143], v87, v173, v[140:143]
	v_mfma_f32_16x16x4_f32 v[128:131], v100, v174, v[128:131]
	v_mfma_f32_16x16x4_f32 v[132:135], v101, v174, v[132:135]
	v_mfma_f32_16x16x4_f32 v[136:139], v102, v174, v[136:139]
	v_mfma_f32_16x16x4_f32 v[140:143], v103, v174, v[140:143]
	v_mfma_f32_16x16x4_f32 v[128:131], v116, v175, v[128:131]
	v_mfma_f32_16x16x4_f32 v[132:135], v117, v175, v[132:135]
	v_mfma_f32_16x16x4_f32 v[136:139], v118, v175, v[136:139]
	v_mfma_f32_16x16x4_f32 v[140:143], v119, v175, v[140:143]
	v_mfma_f32_16x16x4_f32 v[128:131], v72, v176, v[128:131]
	v_mfma_f32_16x16x4_f32 v[132:135], v73, v176, v[132:135]
	v_mfma_f32_16x16x4_f32 v[136:139], v74, v176, v[136:139]
	v_mfma_f32_16x16x4_f32 v[140:143], v75, v176, v[140:143]
	v_mfma_f32_16x16x4_f32 v[128:131], v88, v177, v[128:131]
	v_mfma_f32_16x16x4_f32 v[132:135], v89, v177, v[132:135]
; template <bool HAS_C, bool STORE_STEPS>
; __device__ __forceinline__ void chain16(f32x4 (&acc)[4], const float* Mb, size_t mstride, float* Cb, size_t cstride, int nsteps) {
;     ...
;     for (int c = 0; c < nsteps; ++c) {
;         float* cp = Cb + (size_t)c * cstride;
;         f32x4 q[4];
;         if (HAS_C) {
; #pragma unroll
;             for (int j = 0; j < 4; ++j) q[j] = qn[j];
;             const float* cn = Cb + (size_t)(c + 1 < nsteps ? c + 1 : c) * cstride;
; #pragma unroll
;             for (int j = 0; j < 4; ++j) qn[j] = *(const f32x4*)(cn + 4 * j);
;         }
;         f32x4 mn[16];
;         const float* Mn = Mb + (size_t)(c + 1 < nsteps ? c + 1 : c) * mstride;
; #pragma unroll
;         for (int i = 0; i < 16; ++i) mn[i] = *(const f32x4*)(Mn + (size_t)i * 64);
;         if (STORE_STEPS) {
; #pragma unroll
;             for (int j = 0; j < 4; ++j) *(f32x4*)(cp + 4 * j) = (f32x4){acc[0][j], acc[1][j], acc[2][j], acc[3][j]};
;         }
;         f32x4 na[4];
; #pragma unroll
;         for (int n = 0; n < 4; ++n) na[n] = HAS_C ? (f32x4){q[0][n], q[1][n], q[2][n], q[3][n]} : (f32x4){0.f, 0.f, 0.f, 0.f};
; #pragma unroll
;         for (int n = 0; n < 4; ++n)
; #pragma unroll
;             for (int j = 0; j < 4; ++j) {
;                 const f32x4 a4 = mc[4 * j + n];
; #pragma unroll
;                 for (int np = 0; np < 4; ++np) na[np] = __builtin_amdgcn_mfma_f32_16x16x4f32(a4[np], acc[n][j], na[np], 0, 0, 0);
;             }
; #pragma unroll
;         for (int n = 0; n < 4; ++n) acc[n] = na[n];
; #pragma unroll
;         for (int i = 0; i < 16; ++i) mc[i] = mn[i];
;     }
	v_mfma_f32_16x16x4_f32 v[136:139], v90, v177, v[136:139]
	v_mfma_f32_16x16x4_f32 v[140:143], v91, v177, v[140:143]
	v_mfma_f32_16x16x4_f32 v[128:131], v104, v178, v[128:131]
	v_mfma_f32_16x16x4_f32 v[132:135], v105, v178, v[132:135]
	v_mfma_f32_16x16x4_f32 v[136:139], v106, v178, v[136:139]
	v_mfma_f32_16x16x4_f32 v[140:143], v107, v178, v[140:143]
	v_mfma_f32_16x16x4_f32 v[128:131], v120, v179, v[128:131]
	v_mfma_f32_16x16x4_f32 v[132:135], v121, v179, v[132:135]
	v_mfma_f32_16x16x4_f32 v[136:139], v122, v179, v[136:139]
	v_mfma_f32_16x16x4_f32 v[140:143], v123, v179, v[140:143]
	v_mfma_f32_16x16x4_f32 v[128:131], v76, v180, v[128:131]
	v_mfma_f32_16x16x4_f32 v[132:135], v77, v180, v[132:135]
	v_mfma_f32_16x16x4_f32 v[136:139], v78, v180, v[136:139]
	v_mfma_f32_16x16x4_f32 v[140:143], v79, v180, v[140:143]
	v_mfma_f32_16x16x4_f32 v[128:131], v92, v181, v[128:131]
	v_mfma_f32_16x16x4_f32 v[132:135], v93, v181, v[132:135]
	v_mfma_f32_16x16x4_f32 v[136:139], v94, v181, v[136:139]
	v_mfma_f32_16x16x4_f32 v[140:143], v95, v181, v[140:143]
	v_mfma_f32_16x16x4_f32 v[128:131], v108, v182, v[128:131]
	v_mfma_f32_16x16x4_f32 v[132:135], v109, v182, v[132:135]
	v_mfma_f32_16x16x4_f32 v[136:139], v110, v182, v[136:139]
	v_mfma_f32_16x16x4_f32 v[140:143], v111, v182, v[140:143]
	v_mfma_f32_16x16x4_f32 v[128:131], v124, v183, v[128:131]
	v_mfma_f32_16x16x4_f32 v[132:135], v125, v183, v[132:135]
	v_mfma_f32_16x16x4_f32 v[136:139], v126, v183, v[136:139]
	v_mfma_f32_16x16x4_f32 v[140:143], v127, v183, v[140:143]
	s_mov_b64 s[0:1], s[4:5]
	s_mov_b64 s[2:3], s[6:7]
	s_add_i32 s9, s9, 1
	s_branch .Lp2_l2g_loop
.Lp2_l2g_tail:
	s_bitcmp1_b32 s20, 0
	s_cbranch_scc0 .Lp2_l2g_done
	s_mov_b32 s10, 0x20000
	s_add_u32 s4, s0, s10
	s_addc_u32 s5, s1, 0
	s_add_u32 s6, s2, s10
	s_addc_u32 s7, s3, 0
	global_load_dwordx4 v[64:67], v144, s[4:5]
	global_load_dwordx4 v[68:71], v144, s[4:5] offset:256
	global_load_dwordx4 v[72:75], v144, s[4:5] offset:512
	global_load_dwordx4 v[76:79], v144, s[4:5] offset:768
	global_load_dwordx4 v[80:83], v144, s[4:5] offset:1024
	global_load_dwordx4 v[84:87], v144, s[4:5] offset:1280
	global_load_dwordx4 v[88:91], v144, s[4:5] offset:1536
	global_load_dwordx4 v[92:95], v144, s[4:5] offset:1792
	global_load_dwordx4 v[96:99], v144, s[4:5] offset:2048
	global_load_dwordx4 v[100:103], v144, s[4:5] offset:2304
	global_load_dwordx4 v[104:107], v144, s[4:5] offset:2560
	global_load_dwordx4 v[108:111], v144, s[4:5] offset:2816
	global_load_dwordx4 v[112:115], v144, s[4:5] offset:3072
	global_load_dwordx4 v[116:119], v144, s[4:5] offset:3328
	global_load_dwordx4 v[120:123], v144, s[4:5] offset:3584
	global_load_dwordx4 v[124:127], v144, s[4:5] offset:3840
	global_load_dwordx4 v[200:203], v145, s[6:7]
	global_load_dwordx4 v[204:207], v145, s[6:7] offset:16
	global_load_dwordx4 v[212:215], v145, s[6:7] offset:32
	global_load_dwordx4 v[230:233], v145, s[6:7] offset:48
	s_waitcnt vmcnt(20)
; template <bool HAS_C, bool STORE_STEPS>
; __device__ __forceinline__ void chain16(f32x4 (&acc)[4], const float* Mb, size_t mstride, float* Cb, size_t cstride, int nsteps) {
;     ...
;     for (int c = 0; c < nsteps; ++c) {
;         float* cp = Cb + (size_t)c * cstride;
;         f32x4 q[4];
;         if (HAS_C) {
; #pragma unroll
;             for (int j = 0; j < 4; ++j) q[j] = qn[j];
;             const float* cn = Cb + (size_t)(c + 1 < nsteps ? c + 1 : c) * cstride;
; #pragma unroll
;             for (int j = 0; j < 4; ++j) qn[j] = *(const f32x4*)(cn + 4 * j);
;         }
;         f32x4 mn[16];
;         const float* Mn = Mb + (size_t)(c + 1 < nsteps ? c + 1 : c) * mstride;
; #pragma unroll
;         for (int i = 0; i < 16; ++i) mn[i] = *(const f32x4*)(Mn + (size_t)i * 64);
;         if (STORE_STEPS) {
; #pragma unroll
;             for (int j = 0; j < 4; ++j) *(f32x4*)(cp + 4 * j) = (f32x4){acc[0][j], acc[1][j], acc[2][j], acc[3][j]};
;         }
;         f32x4 na[4];
; #pragma unroll
;         for (int n = 0; n < 4; ++n) na[n] = HAS_C ? (f32x4){q[0][n], q[1][n], q[2][n], q[3][n]} : (f32x4){0.f, 0.f, 0.f, 0.f};
; #pragma unroll
;         for (int n = 0; n < 4; ++n)
; #pragma unroll
;             for (int j = 0; j < 4; ++j) {
;                 const f32x4 a4 = mc[4 * j + n];
; #pragma unroll
;                 for (int np = 0; np < 4; ++np) na[np] = __builtin_amdgcn_mfma_f32_16x16x4f32(a4[np], acc[n][j], na[np], 0, 0, 0);
;             }
; #pragma unroll
;         for (int n = 0; n < 4; ++n) acc[n] = na[n];
; #pragma unroll
;         for (int i = 0; i < 16; ++i) mc[i] = mn[i];
;     }
; __device__ __forceinline__ void stage_rwkv_pass2(const Params& P, int level) {
;     ...
;             if (spread) { const int x = blockIdx.x & 7, j = blockIdx.x >> 3, idx = wave * 32 + j; it = ((idx >> 2) * 8 + x) * 4 + (idx & 3); }
;             const int g = it >> 5, h = (it >> 2) & 7, s = it & 3, v = 16 * s + rho;
;             const float* sg = CG + ((size_t)g * 8 + h) * 4096 + (size_t)v * 64 + 16 * g4;
;             f32x4 q[4];
; #pragma unroll
;             for (int j = 0; j < 4; ++j) q[j] = *(const f32x4*)(sg + 4 * j);
; #pragma unroll
;             for (int n = 0; n < 4; ++n) acc[n] = (f32x4){q[0][n], q[1][n], q[2][n], q[3][n]};
;             const float* Mb = MCM + ((size_t)(g * P2_GS) * 8 + h) * 4096 + (size_t)(16 * g4) * 64 + 4 * rho;
	v_mov_b32_e32 v168, v184
	v_mov_b32_e32 v169, v188
	v_mov_b32_e32 v170, v192
	v_mov_b32_e32 v171, v196
	v_mov_b32_e32 v172, v185
	v_mov_b32_e32 v173, v189
	v_mov_b32_e32 v174, v193
	v_mov_b32_e32 v175, v197
	v_mov_b32_e32 v176, v186
	v_mov_b32_e32 v177, v190
	v_mov_b32_e32 v178, v194
	v_mov_b32_e32 v179, v198
	v_mov_b32_e32 v180, v187
	v_mov_b32_e32 v181, v191
	v_mov_b32_e32 v182, v195
	v_mov_b32_e32 v183, v199
	v_mfma_f32_16x16x4_f32 v[168:171], v0, v128, v[168:171]
	v_mfma_f32_16x16x4_f32 v[172:175], v1, v128, v[172:175]
	v_mfma_f32_16x16x4_f32 v[176:179], v2, v128, v[176:179]
	v_mfma_f32_16x16x4_f32 v[180:183], v3, v128, v[180:183]
	v_mfma_f32_16x16x4_f32 v[168:171], v16, v129, v[168:171]
	v_mfma_f32_16x16x4_f32 v[172:175], v17, v129, v[172:175]
	v_mfma_f32_16x16x4_f32 v[176:179], v18, v129, v[176:179]
	v_mfma_f32_16x16x4_f32 v[180:183], v19, v129, v[180:183]
	v_mfma_f32_16x16x4_f32 v[168:171], v32, v130, v[168:171]
	v_mfma_f32_16x16x4_f32 v[172:175], v33, v130, v[172:175]
	v_mfma_f32_16x16x4_f32 v[176:179], v34, v130, v[176:179]
	v_mfma_f32_16x16x4_f32 v[180:183], v35, v130, v[180:183]
	v_mfma_f32_16x16x4_f32 v[168:171], v48, v131, v[168:171]
	v_mfma_f32_16x16x4_f32 v[172:175], v49, v131, v[172:175]
	v_mfma_f32_16x16x4_f32 v[176:179], v50, v131, v[176:179]
	v_mfma_f32_16x16x4_f32 v[180:183], v51, v131, v[180:183]
	v_mfma_f32_16x16x4_f32 v[168:171], v4, v132, v[168:171]
	v_mfma_f32_16x16x4_f32 v[172:175], v5, v132, v[172:175]
	v_mfma_f32_16x16x4_f32 v[176:179], v6, v132, v[176:179]
	v_mfma_f32_16x16x4_f32 v[180:183], v7, v132, v[180:183]
	v_mfma_f32_16x16x4_f32 v[168:171], v20, v133, v[168:171]
	v_mfma_f32_16x16x4_f32 v[172:175], v21, v133, v[172:175]
	v_mfma_f32_16x16x4_f32 v[176:179], v22, v133, v[176:179]
	v_mfma_f32_16x16x4_f32 v[180:183], v23, v133, v[180:183]
	v_mfma_f32_16x16x4_f32 v[168:171], v36, v134, v[168:171]
	v_mfma_f32_16x16x4_f32 v[172:175], v37, v134, v[172:175]
	v_mfma_f32_16x16x4_f32 v[176:179], v38, v134, v[176:179]
	v_mfma_f32_16x16x4_f32 v[180:183], v39, v134, v[180:183]
	v_mfma_f32_16x16x4_f32 v[168:171], v52, v135, v[168:171]
	v_mfma_f32_16x16x4_f32 v[172:175], v53, v135, v[172:175]
	v_mfma_f32_16x16x4_f32 v[176:179], v54, v135, v[176:179]
	v_mfma_f32_16x16x4_f32 v[180:183], v55, v135, v[180:183]
	v_mfma_f32_16x16x4_f32 v[168:171], v8, v136, v[168:171]
	v_mfma_f32_16x16x4_f32 v[172:175], v9, v136, v[172:175]
	v_mfma_f32_16x16x4_f32 v[176:179], v10, v136, v[176:179]
	v_mfma_f32_16x16x4_f32 v[180:183], v11, v136, v[180:183]
	v_mfma_f32_16x16x4_f32 v[168:171], v24, v137, v[168:171]
	v_mfma_f32_16x16x4_f32 v[172:175], v25, v137, v[172:175]
	v_mfma_f32_16x16x4_f32 v[176:179], v26, v137, v[176:179]
	v_mfma_f32_16x16x4_f32 v[180:183], v27, v137, v[180:183]
	v_mfma_f32_16x16x4_f32 v[168:171], v40, v138, v[168:171]
	v_mfma_f32_16x16x4_f32 v[172:175], v41, v138, v[172:175]
	v_mfma_f32_16x16x4_f32 v[176:179], v42, v138, v[176:179]
	v_mfma_f32_16x16x4_f32 v[180:183], v43, v138, v[180:183]
	v_mfma_f32_16x16x4_f32 v[168:171], v56, v139, v[168:171]
	v_mfma_f32_16x16x4_f32 v[172:175], v57, v139, v[172:175]
	v_mfma_f32_16x16x4_f32 v[176:179], v58, v139, v[176:179]
	v_mfma_f32_16x16x4_f32 v[180:183], v59, v139, v[180:183]
	v_mfma_f32_16x16x4_f32 v[168:171], v12, v140, v[168:171]
	v_mfma_f32_16x16x4_f32 v[172:175], v13, v140, v[172:175]
	v_mfma_f32_16x16x4_f32 v[176:179], v14, v140, v[176:179]
	v_mfma_f32_16x16x4_f32 v[180:183], v15, v140, v[180:183]
	v_mfma_f32_16x16x4_f32 v[168:171], v28, v141, v[168:171]
	v_mfma_f32_16x16x4_f32 v[172:175], v29, v141, v[172:175]
	v_mfma_f32_16x16x4_f32 v[176:179], v30, v141, v[176:179]
	v_mfma_f32_16x16x4_f32 v[180:183], v31, v141, v[180:183]
	v_mfma_f32_16x16x4_f32 v[168:171], v44, v142, v[168:171]
	v_mfma_f32_16x16x4_f32 v[172:175], v45, v142, v[172:175]
	v_mfma_f32_16x16x4_f32 v[176:179], v46, v142, v[176:179]
	v_mfma_f32_16x16x4_f32 v[180:183], v47, v142, v[180:183]
	v_mfma_f32_16x16x4_f32 v[168:171], v60, v143, v[168:171]
	v_mfma_f32_16x16x4_f32 v[172:175], v61, v143, v[172:175]
	v_mfma_f32_16x16x4_f32 v[176:179], v62, v143, v[176:179]
	v_mfma_f32_16x16x4_f32 v[180:183], v63, v143, v[180:183]
	s_mov_b64 s[0:1], s[4:5]
	s_mov_b64 s[2:3], s[6:7]
	s_nop 7
	s_nop 3
	v_mov_b32_e32 v128, v168
	v_mov_b32_e32 v129, v169
	v_mov_b32_e32 v130, v170
	v_mov_b32_e32 v131, v171
	v_mov_b32_e32 v132, v172
	v_mov_b32_e32 v133, v173
	v_mov_b32_e32 v134, v174
	v_mov_b32_e32 v135, v175
	v_mov_b32_e32 v136, v176
	v_mov_b32_e32 v137, v177
	v_mov_b32_e32 v138, v178
	v_mov_b32_e32 v139, v179
	v_mov_b32_e32 v140, v180
	v_mov_b32_e32 v141, v181
	v_mov_b32_e32 v142, v182
	v_mov_b32_e32 v143, v183
.Lp2_l2g_done:
	s_lshl_b32 s18, s14, 7
	s_add_i32 s18, s18, s15
	s_lshl_b32 s18, s18, 14
	s_add_u32 s0, s72, 0x10880000
	s_addc_u32 s1, s73, 0
	s_add_u32 s0, s0, s18
	s_addc_u32 s1, s1, 0
	s_add_u32 s2, s72, 0x12880000
	s_addc_u32 s3, s73, 0
	s_add_u32 s2, s2, s18
	s_addc_u32 s3, s3, 0
	s_add_u32 s2, s2, s19
	s_addc_u32 s3, s3, 0
	global_load_dwordx4 v[0:3], v144, s[0:1]
	global_load_dwordx4 v[4:7], v144, s[0:1] offset:256
	global_load_dwordx4 v[8:11], v144, s[0:1] offset:512
	global_load_dwordx4 v[12:15], v144, s[0:1] offset:768
	global_load_dwordx4 v[16:19], v144, s[0:1] offset:1024
	global_load_dwordx4 v[20:23], v144, s[0:1] offset:1280
	global_load_dwordx4 v[24:27], v144, s[0:1] offset:1536
	global_load_dwordx4 v[28:31], v144, s[0:1] offset:1792
	global_load_dwordx4 v[32:35], v144, s[0:1] offset:2048
	global_load_dwordx4 v[36:39], v144, s[0:1] offset:2304
	global_load_dwordx4 v[40:43], v144, s[0:1] offset:2560
	global_load_dwordx4 v[44:47], v144, s[0:1] offset:2816
	global_load_dwordx4 v[48:51], v144, s[0:1] offset:3072
	global_load_dwordx4 v[52:55], v144, s[0:1] offset:3328
	global_load_dwordx4 v[56:59], v144, s[0:1] offset:3584
	global_load_dwordx4 v[60:63], v144, s[0:1] offset:3840
	global_load_dwordx4 v[184:187], v145, s[2:3]
	global_load_dwordx4 v[188:191], v145, s[2:3] offset:16
	global_load_dwordx4 v[192:195], v145, s[2:3] offset:32
	global_load_dwordx4 v[196:199], v145, s[2:3] offset:48
	s_mov_b32 s9, 0
